# S5 pass 2 incoming-state: all carry loads issued up front (one round trip) and a scalar-bounded unrolled chain instead of 8-at-a-time load/wait batches
# baseline (speedup 1.0000x reference)
; __device__ __forceinline__ unsigned pk2(float lo, float hi) { const hf32x2 v = {lo, hi}; return __builtin_bit_cast(unsigned, __builtin_convertvector(v, hbf16x2)); }
; __device__ __forceinline__ void s5_lane_params(PP p, int l, int g, int n, S5Lane& q) {
;     const int gi = (l * 32 + g) * 64 + n;
;     const float lr = p->in[6][gi], li = p->in[7][gi], dt = expf(p->in[8][l * 32 + g]);
;     const float mag = expf(lr * dt);
;     float sn, cs; sincosf(li * dt, &sn, &cs);
;     q.ar = mag * cs; q.ai = mag * sn;
;     const float den = lr * lr + li * li, nr = q.ar - 1.0f, ni = q.ai;
;     const float fr_ = (nr * lr + ni * li) / den, fi_ = (ni * lr - nr * li) / den;
;     const f32x4* bre = (const f32x4*)(p->in[9] + (size_t)gi * 16); const f32x4* bim = (const f32x4*)(p->in[10] + (size_t)gi * 16);
; #pragma unroll
;     for (int c4 = 0; c4 < 4; ++c4) { const f32x4 br = bre[c4], bi = bim[c4];
; #pragma unroll
;         for (int e = 0; e < 4; ++e) { q.bb[c4 * 4 + e] = (f32x2){fr_ * br[e] - fi_ * bi[e], fr_ * bi[e] + fi_ * br[e]}; } }
; __device__ __forceinline__ void s5_write_bbl(const S5Lane& q, bf16_t* bbL, int lane) {
;     u32x4 re0, re1, im0, im1;
;     re0.x = pk2(q.bb[0].x, q.bb[1].x); re0.y = pk2(q.bb[2].x, q.bb[3].x); re0.z = pk2(q.bb[4].x, q.bb[5].x); re0.w = pk2(q.bb[6].x, q.bb[7].x);
;     re1.x = pk2(q.bb[8].x, q.bb[9].x); re1.y = pk2(q.bb[10].x, q.bb[11].x); re1.z = pk2(q.bb[12].x, q.bb[13].x); re1.w = pk2(q.bb[14].x, q.bb[15].x);
;     im0.x = pk2(q.bb[0].y, q.bb[1].y); im0.y = pk2(q.bb[2].y, q.bb[3].y); im0.z = pk2(q.bb[4].y, q.bb[5].y); im0.w = pk2(q.bb[6].y, q.bb[7].y);
;     im1.x = pk2(q.bb[8].y, q.bb[9].y); im1.y = pk2(q.bb[10].y, q.bb[11].y); im1.z = pk2(q.bb[12].y, q.bb[13].y); im1.w = pk2(q.bb[14].y, q.bb[15].y);
;     *(u32x4*)(bbL + lane * 16) = re0; *(u32x4*)(bbL + lane * 16 + 8) = re1;
;     *(u32x4*)(bbL + (64 + lane) * 16) = im0; *(u32x4*)(bbL + (64 + lane) * 16 + 8) = im1;
.LBB0_692:
	s_or_b64 exec, exec, s[2:3]
	s_waitcnt vmcnt(8)
	v_mul_f32_e32 v84, v90, v87
	v_mul_f32_e32 v85, 0x3fb8aa3b, v84
	s_mov_b32 s2, 0x3fb8aa3b
	v_fma_f32 v87, v84, s2, -v85
	v_rndne_f32_e32 v96, v85
	v_fmac_f32_e32 v87, 0x32a5705f, v84
	v_sub_f32_e32 v85, v85, v96
	v_add_f32_e32 v85, v85, v87
	v_exp_f32_e32 v85, v85
	v_cvt_i32_f32_e32 v87, v96
	s_mov_b32 s2, 0xc2ce8ed0
	v_cmp_ngt_f32_e32 vcc, s2, v84
	s_mov_b32 s2, 0x42b17218
	v_ldexp_f32 v85, v85, v87
	v_cndmask_b32_e32 v85, 0, v85, vcc
	v_cmp_nlt_f32_e32 vcc, s2, v84
	v_mul_f32_e32 v84, v89, v89
	v_fmamk_f32 v96, v84, 0xb94c1982, v233
	v_fmaak_f32 v96, v84, v96, 0xbe2aaa9d
	v_mul_f32_e32 v96, v84, v96
	v_fmac_f32_e32 v89, v89, v96
	v_fmamk_f32 v96, v84, 0x37d75334, v227
	v_fmaak_f32 v96, v84, v96, 0x3d2aabf7
	v_fmaak_f32 v96, v84, v96, 0xbf000004
	v_fma_f32 v84, v84, v96, 1.0
	v_lshlrev_b32_e32 v96, 30, v95
	v_and_b32_e32 v95, 1, v95
	v_cndmask_b32_e32 v85, v231, v85, vcc
	v_cmp_eq_u32_e32 vcc, 0, v95
	v_xor_b32_e32 v88, v88, v86
	v_readlane_b32 s2, v255, 9
	v_cndmask_b32_e32 v95, v84, v89, vcc
	v_xor_b32_e32 v89, 0x80000000, v89
	v_cndmask_b32_e32 v84, v89, v84, vcc
	v_and_b32_e32 v97, 0x80000000, v96
	v_xor_b32_e32 v88, v88, v95
	v_bitop3_b32 v84, v84, v96, s2 bitop3:0x78
	s_movk_i32 s2, 0x1f8
	v_xor_b32_e32 v88, v88, v97
	v_cmp_class_f32_e64 vcc, v86, s2
	v_mov_b32_e32 v87, 0
	v_readlane_b32 s3, v255, 10
	v_cndmask_b32_e32 v86, v234, v84, vcc
	v_cndmask_b32_e32 v88, v234, v88, vcc
	v_mul_f32_e32 v89, v85, v88
	v_fma_f32 v88, v85, v86, -1.0
	v_pk_mul_f32 v[96:97], v[90:91], v[88:89]
	v_mul_f32_e32 v84, v85, v86
	v_add_f32_e32 v85, v96, v97
	v_mov_b32_e32 v96, v89
	v_mov_b32_e32 v97, v90
	v_pk_mul_f32 v[96:97], v[90:91], v[96:97] op_sel_hi:[0,1]
	v_mov_b32_e32 v86, v91
	v_mov_b32_e32 v90, v88
	v_pk_mul_f32 v[90:91], v[86:87], v[90:91] op_sel_hi:[0,1]
	v_add_f32_e32 v88, v97, v91
	v_div_scale_f32 v86, s[2:3], v88, v88, v85
	v_rcp_f32_e32 v91, v86
	s_nop 0
	v_fma_f32 v95, -v86, v91, 1.0
	v_fmac_f32_e32 v91, v95, v91
	v_div_scale_f32 v95, vcc, v85, v88, v85
	v_mul_f32_e32 v97, v95, v91
	v_fma_f32 v99, -v86, v97, v95
	v_fmac_f32_e32 v97, v99, v91
	v_fma_f32 v86, -v86, v97, v95
	v_div_fmas_f32 v86, v86, v91, v97
	v_div_fixup_f32 v86, v86, v88, v85
	v_sub_f32_e32 v85, v96, v90
	v_div_scale_f32 v90, s[2:3], v88, v88, v85
	v_rcp_f32_e32 v91, v90
	v_lshlrev_b32_e32 v99, 5, v98
	v_fma_f32 v95, -v90, v91, 1.0
	v_fmac_f32_e32 v91, v95, v91
	v_div_scale_f32 v95, vcc, v85, v88, v85
	v_mul_f32_e32 v96, v95, v91
	v_fma_f32 v97, -v90, v96, v95
	v_fmac_f32_e32 v96, v97, v91
	v_fma_f32 v90, -v90, v96, v95
	v_div_fmas_f32 v90, v90, v91, v96
	v_div_fixup_f32 v88, v90, v88, v85
	s_waitcnt vmcnt(0)
	v_pk_mul_f32 v[90:91], v[22:23], v[88:89] op_sel_hi:[1,0]
	v_pk_mul_f32 v[96:97], v[24:25], v[88:89] op_sel_hi:[1,0]
	v_pk_fma_f32 v[90:91], v[34:35], v[86:87], v[90:91] op_sel_hi:[1,0,1] neg_lo:[0,0,1] neg_hi:[0,0,1]
	v_pk_mul_f32 v[34:35], v[34:35], v[88:89] op_sel_hi:[1,0]
	v_pk_mul_f32 v[102:103], v[18:19], v[88:89] op_sel_hi:[1,0]
	v_pk_mul_f32 v[104:105], v[20:21], v[88:89] op_sel_hi:[1,0]
	v_pk_mul_f32 v[106:107], v[10:11], v[88:89] op_sel_hi:[1,0]
	v_pk_mul_f32 v[108:109], v[12:13], v[88:89] op_sel_hi:[1,0]
	v_pk_mul_f32 v[110:111], v[6:7], v[88:89] op_sel_hi:[1,0]
	v_pk_mul_f32 v[112:113], v[8:9], v[88:89] op_sel_hi:[1,0]
	v_pk_fma_f32 v[96:97], v[36:37], v[86:87], v[96:97] op_sel_hi:[1,0,1] neg_lo:[0,0,1] neg_hi:[0,0,1]
	v_pk_mul_f32 v[36:37], v[36:37], v[88:89] op_sel_hi:[1,0]
	v_pk_fma_f32 v[102:103], v[30:31], v[86:87], v[102:103] op_sel_hi:[1,0,1] neg_lo:[0,0,1] neg_hi:[0,0,1]
	v_pk_mul_f32 v[30:31], v[30:31], v[88:89] op_sel_hi:[1,0]
	v_pk_fma_f32 v[104:105], v[32:33], v[86:87], v[104:105] op_sel_hi:[1,0,1] neg_lo:[0,0,1] neg_hi:[0,0,1]
	v_pk_mul_f32 v[32:33], v[32:33], v[88:89] op_sel_hi:[1,0]
	v_pk_fma_f32 v[106:107], v[26:27], v[86:87], v[106:107] op_sel_hi:[1,0,1] neg_lo:[0,0,1] neg_hi:[0,0,1]
	v_pk_mul_f32 v[26:27], v[26:27], v[88:89] op_sel_hi:[1,0]
	v_pk_fma_f32 v[108:109], v[28:29], v[86:87], v[108:109] op_sel_hi:[1,0,1] neg_lo:[0,0,1] neg_hi:[0,0,1]
	v_pk_mul_f32 v[28:29], v[28:29], v[88:89] op_sel_hi:[1,0]
	v_pk_fma_f32 v[110:111], v[14:15], v[86:87], v[110:111] op_sel_hi:[1,0,1] neg_lo:[0,0,1] neg_hi:[0,0,1]
	v_pk_mul_f32 v[14:15], v[14:15], v[88:89] op_sel_hi:[1,0]
	v_pk_fma_f32 v[112:113], v[16:17], v[86:87], v[112:113] op_sel_hi:[1,0,1] neg_lo:[0,0,1] neg_hi:[0,0,1]
	v_pk_mul_f32 v[16:17], v[16:17], v[88:89] op_sel_hi:[1,0]
	v_pk_fma_f32 v[22:23], v[22:23], v[86:87], v[34:35] op_sel_hi:[1,0,1]
	v_pk_fma_f32 v[24:25], v[24:25], v[86:87], v[36:37] op_sel_hi:[1,0,1]
	v_pk_fma_f32 v[18:19], v[18:19], v[86:87], v[30:31] op_sel_hi:[1,0,1]
	v_pk_fma_f32 v[20:21], v[20:21], v[86:87], v[32:33] op_sel_hi:[1,0,1]
	v_pk_fma_f32 v[26:27], v[10:11], v[86:87], v[26:27] op_sel_hi:[1,0,1]
	v_pk_fma_f32 v[28:29], v[12:13], v[86:87], v[28:29] op_sel_hi:[1,0,1]
	v_pk_fma_f32 v[30:31], v[6:7], v[86:87], v[14:15] op_sel_hi:[1,0,1]
	v_pk_fma_f32 v[32:33], v[8:9], v[86:87], v[16:17] op_sel_hi:[1,0,1]
	v_cvt_pk_bf16_f32 v6, v90, v91
	v_cvt_pk_bf16_f32 v7, v96, v97
	v_cvt_pk_bf16_f32 v8, v102, v103
	v_cvt_pk_bf16_f32 v9, v104, v105
	v_cvt_pk_bf16_f32 v14, v22, v23
	v_add_u32_e32 v22, 0, v99
	v_cmp_lt_i32_e32 vcc, 0, v94
	v_lshlrev_b32_e32 v90, 3, v98
	v_mov_b32_e32 v86, v87
	v_cvt_pk_bf16_f32 v10, v106, v107
	v_cvt_pk_bf16_f32 v11, v108, v109
	v_cvt_pk_bf16_f32 v12, v110, v111
	v_cvt_pk_bf16_f32 v13, v112, v113
	v_cvt_pk_bf16_f32 v15, v24, v25
	v_cvt_pk_bf16_f32 v16, v18, v19
	v_cvt_pk_bf16_f32 v17, v20, v21
	v_cvt_pk_bf16_f32 v18, v26, v27
	v_cvt_pk_bf16_f32 v19, v28, v29
	v_cvt_pk_bf16_f32 v20, v30, v31
	v_cvt_pk_bf16_f32 v21, v32, v33
	ds_write_b128 v22, v[6:9]
	ds_write_b128 v22, v[10:13] offset:16
	ds_write_b128 v22, v[14:17] offset:2048
	ds_write_b128 v22, v[18:21] offset:2064
	s_and_saveexec_b64 s[52:53], vcc
	s_cbranch_execz .LBB0_710
; __device__ __forceinline__ void s5_pass2_item(PP p, unsigned char* shm, int item, int l) {
;     ...
;     float pr = q.ar, pi = q.ai;
; #pragma unroll
;     for (int s = 0; s < 6; ++s) { const float nr = pr * pr - pi * pi, ni = 2.f * pr * pi; pr = nr; pi = ni; }
;     f32x2 x = (f32x2){0.f, 0.f};
;     const f32x2* carry = (const f32x2*)((const float*)(p->ws + WS_CARRY) + ((size_t)((b * 32 + g) * 32) * 64 + lane) * 2);
;     for (int i0 = 0; i0 < j; i0 += 8) {
;         f32x2 sv[8];
; #pragma unroll
;         for (int e = 0; e < 8; ++e) sv[e] = (i0 + e < j) ? carry[(size_t)(i0 + e) * 64] : (f32x2){0.f, 0.f};
; #pragma unroll
;         for (int e = 0; e < 8; ++e) if (i0 + e < j) { const f32x2 rot = (f32x2){-x.y, x.x}; x = (x * pr + rot * pi) + sv[e]; }
	v_mul_f32_e32 v6, v89, v89
	v_add_f32_e32 v7, v84, v84
	v_fma_f32 v6, v84, v84, -v6
	v_mul_f32_e32 v8, v89, v7
	v_mov_b32_e32 v233, v6
	v_pk_mul_f32 v[10:11], v[6:7], v[232:233] op_sel_hi:[0,1]
	v_mul_f32_e32 v9, v8, v8
	v_pk_mul_f32 v[10:11], v[10:11], v[8:9]
	v_pk_fma_f32 v[6:7], v[6:7], v[232:233], v[8:9] op_sel_hi:[0,1,1] neg_lo:[0,0,1] neg_hi:[0,0,1]
	v_mov_b32_e32 v11, v7
	v_mul_f32_e32 v6, v7, v7
	v_add_f32_e32 v9, v7, v7
	v_pk_fma_f32 v[6:7], v[10:11], v[10:11], v[6:7] op_sel_hi:[1,1,0] neg_lo:[1,0,0] neg_hi:[1,0,0]
	s_lshl_b32 s2, s40, 10
	v_mul_f32_e32 v7, v10, v9
	v_mul_f32_e32 v10, v6, v6
	v_pk_fma_f32 v[10:11], v[6:7], v[6:7], v[10:11] op_sel_hi:[1,1,0] neg_lo:[1,0,0] neg_hi:[1,0,0]
	s_lshl_b32 s3, s16, 5
	v_add_f32_e32 v8, v6, v6
	v_mov_b32_e32 v6, v7
	v_mov_b32_e32 v7, v11
	v_mov_b32_e32 v9, v11
	s_add_i32 s2, s3, s2
	v_pk_mul_f32 v[6:7], v[6:7], v[8:9]
	s_ashr_i32 s3, s2, 31
	v_pk_mov_b32 v[8:9], v[10:11], v[6:7] op_sel:[1,0]
	v_mov_b32_e32 v233, v6
	s_lshl_b64 s[2:3], s[2:3], 9
	v_pk_mul_f32 v[10:11], v[8:9], v[232:233]
	s_add_u32 s2, s28, s2
	v_pk_mul_f32 v[10:11], v[6:7], v[10:11]
	v_pk_fma_f32 v[6:7], v[8:9], v[232:233], v[6:7] neg_lo:[1,0,0] neg_hi:[1,0,0]
	v_mov_b32_e32 v91, v1
	v_mov_b32_e32 v11, v7
	v_add_f32_e32 v6, v7, v7
	s_addc_u32 s3, s29, s3
	v_mul_f32_e32 v6, v10, v6
	v_pk_mul_f32 v[8:9], v[10:11], v[10:11]
	v_lshl_add_u64 v[10:11], s[2:3], 0, v[90:91]
	s_mov_b64 s[2:3], 0x31ac0e00
	v_mov_b32_e32 v86, 0
	v_mov_b32_e32 v30, 0x3c0881c4
	v_pk_add_f32 v[8:9], v[8:9], v[8:9] op_sel:[1,0] op_sel_hi:[1,0] neg_lo:[0,1] neg_hi:[0,1]
	v_mov_b32_e32 v7, v6
	v_lshl_add_u64 v[10:11], v[10:11], 0, s[2:3]
	s_mov_b32 s20, 0
	s_mov_b64 s[2:3], 0
	v_mov_b32_e32 v87, v86
	v_readfirstlane_b32 s20, v94
	global_load_dwordx2 v[140:141], v[10:11], off offset:-3584
	global_load_dwordx2 v[142:143], v[10:11], off offset:-3072
	global_load_dwordx2 v[144:145], v[10:11], off offset:-2560
	global_load_dwordx2 v[146:147], v[10:11], off offset:-2048
	global_load_dwordx2 v[148:149], v[10:11], off offset:-1536
	global_load_dwordx2 v[150:151], v[10:11], off offset:-1024
	global_load_dwordx2 v[152:153], v[10:11], off offset:-512
	global_load_dwordx2 v[154:155], v[10:11], off
	s_cmp_le_u32 s20, 8
	s_cbranch_scc1 .Ls5c_ld_done
	s_mov_b64 s[16:17], 0x1000
	v_lshl_add_u64 v[130:131], v[10:11], 0, s[16:17]
	global_load_dwordx2 v[156:157], v[130:131], off offset:-3584
	global_load_dwordx2 v[158:159], v[130:131], off offset:-3072
	global_load_dwordx2 v[160:161], v[130:131], off offset:-2560
	global_load_dwordx2 v[162:163], v[130:131], off offset:-2048
	global_load_dwordx2 v[164:165], v[130:131], off offset:-1536
	global_load_dwordx2 v[166:167], v[130:131], off offset:-1024
	global_load_dwordx2 v[168:169], v[130:131], off offset:-512
	global_load_dwordx2 v[170:171], v[130:131], off
	s_cmp_le_u32 s20, 16
	s_cbranch_scc1 .Ls5c_ld_done
	s_mov_b64 s[16:17], 0x2000
	v_lshl_add_u64 v[132:133], v[10:11], 0, s[16:17]
	global_load_dwordx2 v[180:181], v[132:133], off offset:-3584
	global_load_dwordx2 v[182:183], v[132:133], off offset:-3072
	global_load_dwordx2 v[184:185], v[132:133], off offset:-2560
	global_load_dwordx2 v[186:187], v[132:133], off offset:-2048
	global_load_dwordx2 v[188:189], v[132:133], off offset:-1536
	global_load_dwordx2 v[190:191], v[132:133], off offset:-1024
	global_load_dwordx2 v[192:193], v[132:133], off offset:-512
	global_load_dwordx2 v[194:195], v[132:133], off
	s_cmp_le_u32 s20, 24
	s_cbranch_scc1 .Ls5c_ld_done
	s_mov_b64 s[16:17], 0x3000
	v_lshl_add_u64 v[134:135], v[10:11], 0, s[16:17]
	global_load_dwordx2 v[196:197], v[134:135], off offset:-3584
	global_load_dwordx2 v[198:199], v[134:135], off offset:-3072
	global_load_dwordx2 v[200:201], v[134:135], off offset:-2560
	global_load_dwordx2 v[202:203], v[134:135], off offset:-2048
	global_load_dwordx2 v[204:205], v[134:135], off offset:-1536
	global_load_dwordx2 v[206:207], v[134:135], off offset:-1024
	global_load_dwordx2 v[208:209], v[134:135], off offset:-512
	global_load_dwordx2 v[210:211], v[134:135], off
.Ls5c_ld_done:
	s_waitcnt vmcnt(0)
	v_xor_b32_e32 v28, 0x80000000, v87
	v_mov_b32_e32 v29, v86
	v_pk_mul_f32 v[28:29], v[6:7], v[28:29]
	s_nop 0
	v_pk_fma_f32 v[28:29], v[8:9], v[86:87], v[28:29]
	s_nop 0
	v_pk_add_f32 v[86:87], v[28:29], v[140:141]
	s_cmp_le_u32 s20, 1
	s_cbranch_scc1 .Ls5c_done
	v_xor_b32_e32 v28, 0x80000000, v87
	v_mov_b32_e32 v29, v86
	v_pk_mul_f32 v[28:29], v[6:7], v[28:29]
	s_nop 0
	v_pk_fma_f32 v[28:29], v[8:9], v[86:87], v[28:29]
	s_nop 0
	v_pk_add_f32 v[86:87], v[28:29], v[142:143]
	s_cmp_le_u32 s20, 2
	s_cbranch_scc1 .Ls5c_done
	v_xor_b32_e32 v28, 0x80000000, v87
	v_mov_b32_e32 v29, v86
	v_pk_mul_f32 v[28:29], v[6:7], v[28:29]
	s_nop 0
	v_pk_fma_f32 v[28:29], v[8:9], v[86:87], v[28:29]
	s_nop 0
	v_pk_add_f32 v[86:87], v[28:29], v[144:145]
	s_cmp_le_u32 s20, 3
	s_cbranch_scc1 .Ls5c_done
	v_xor_b32_e32 v28, 0x80000000, v87
	v_mov_b32_e32 v29, v86
	v_pk_mul_f32 v[28:29], v[6:7], v[28:29]
	s_nop 0
	v_pk_fma_f32 v[28:29], v[8:9], v[86:87], v[28:29]
	s_nop 0
	v_pk_add_f32 v[86:87], v[28:29], v[146:147]
	s_cmp_le_u32 s20, 4
	s_cbranch_scc1 .Ls5c_done
	v_xor_b32_e32 v28, 0x80000000, v87
	v_mov_b32_e32 v29, v86
	v_pk_mul_f32 v[28:29], v[6:7], v[28:29]
	s_nop 0
	v_pk_fma_f32 v[28:29], v[8:9], v[86:87], v[28:29]
	s_nop 0
	v_pk_add_f32 v[86:87], v[28:29], v[148:149]
	s_cmp_le_u32 s20, 5
	s_cbranch_scc1 .Ls5c_done
	v_xor_b32_e32 v28, 0x80000000, v87
	v_mov_b32_e32 v29, v86
	v_pk_mul_f32 v[28:29], v[6:7], v[28:29]
	s_nop 0
	v_pk_fma_f32 v[28:29], v[8:9], v[86:87], v[28:29]
	s_nop 0
	v_pk_add_f32 v[86:87], v[28:29], v[150:151]
	s_cmp_le_u32 s20, 6
	s_cbranch_scc1 .Ls5c_done
; __device__ __forceinline__ void s5_pass2_item(PP p, unsigned char* shm, int item, int l) {
;     ...
;     for (int i0 = 0; i0 < j; i0 += 8) {
;         f32x2 sv[8];
; #pragma unroll
;         for (int e = 0; e < 8; ++e) sv[e] = (i0 + e < j) ? carry[(size_t)(i0 + e) * 64] : (f32x2){0.f, 0.f};
; #pragma unroll
;         for (int e = 0; e < 8; ++e) if (i0 + e < j) { const f32x2 rot = (f32x2){-x.y, x.x}; x = (x * pr + rot * pi) + sv[e]; }
;     }
	v_xor_b32_e32 v28, 0x80000000, v87
	v_mov_b32_e32 v29, v86
	v_pk_mul_f32 v[28:29], v[6:7], v[28:29]
	s_nop 0
	v_pk_fma_f32 v[28:29], v[8:9], v[86:87], v[28:29]
	s_nop 0
	v_pk_add_f32 v[86:87], v[28:29], v[152:153]
	s_cmp_le_u32 s20, 7
	s_cbranch_scc1 .Ls5c_done
	v_xor_b32_e32 v28, 0x80000000, v87
	v_mov_b32_e32 v29, v86
	v_pk_mul_f32 v[28:29], v[6:7], v[28:29]
	s_nop 0
	v_pk_fma_f32 v[28:29], v[8:9], v[86:87], v[28:29]
	s_nop 0
	v_pk_add_f32 v[86:87], v[28:29], v[154:155]
	s_cmp_le_u32 s20, 8
	s_cbranch_scc1 .Ls5c_done
	v_xor_b32_e32 v28, 0x80000000, v87
	v_mov_b32_e32 v29, v86
	v_pk_mul_f32 v[28:29], v[6:7], v[28:29]
	s_nop 0
	v_pk_fma_f32 v[28:29], v[8:9], v[86:87], v[28:29]
	s_nop 0
	v_pk_add_f32 v[86:87], v[28:29], v[156:157]
	s_cmp_le_u32 s20, 9
	s_cbranch_scc1 .Ls5c_done
	v_xor_b32_e32 v28, 0x80000000, v87
	v_mov_b32_e32 v29, v86
	v_pk_mul_f32 v[28:29], v[6:7], v[28:29]
	s_nop 0
	v_pk_fma_f32 v[28:29], v[8:9], v[86:87], v[28:29]
	s_nop 0
	v_pk_add_f32 v[86:87], v[28:29], v[158:159]
	s_cmp_le_u32 s20, 10
	s_cbranch_scc1 .Ls5c_done
	v_xor_b32_e32 v28, 0x80000000, v87
	v_mov_b32_e32 v29, v86
	v_pk_mul_f32 v[28:29], v[6:7], v[28:29]
	s_nop 0
	v_pk_fma_f32 v[28:29], v[8:9], v[86:87], v[28:29]
	s_nop 0
	v_pk_add_f32 v[86:87], v[28:29], v[160:161]
	s_cmp_le_u32 s20, 11
	s_cbranch_scc1 .Ls5c_done
	v_xor_b32_e32 v28, 0x80000000, v87
	v_mov_b32_e32 v29, v86
	v_pk_mul_f32 v[28:29], v[6:7], v[28:29]
	s_nop 0
	v_pk_fma_f32 v[28:29], v[8:9], v[86:87], v[28:29]
	s_nop 0
	v_pk_add_f32 v[86:87], v[28:29], v[162:163]
	s_cmp_le_u32 s20, 12
	s_cbranch_scc1 .Ls5c_done
	v_xor_b32_e32 v28, 0x80000000, v87
	v_mov_b32_e32 v29, v86
	v_pk_mul_f32 v[28:29], v[6:7], v[28:29]
	s_nop 0
	v_pk_fma_f32 v[28:29], v[8:9], v[86:87], v[28:29]
	s_nop 0
	v_pk_add_f32 v[86:87], v[28:29], v[164:165]
	s_cmp_le_u32 s20, 13
	s_cbranch_scc1 .Ls5c_done
	v_xor_b32_e32 v28, 0x80000000, v87
	v_mov_b32_e32 v29, v86
	v_pk_mul_f32 v[28:29], v[6:7], v[28:29]
	s_nop 0
	v_pk_fma_f32 v[28:29], v[8:9], v[86:87], v[28:29]
	s_nop 0
	v_pk_add_f32 v[86:87], v[28:29], v[166:167]
	s_cmp_le_u32 s20, 14
	s_cbranch_scc1 .Ls5c_done
	v_xor_b32_e32 v28, 0x80000000, v87
	v_mov_b32_e32 v29, v86
	v_pk_mul_f32 v[28:29], v[6:7], v[28:29]
	s_nop 0
	v_pk_fma_f32 v[28:29], v[8:9], v[86:87], v[28:29]
	s_nop 0
	v_pk_add_f32 v[86:87], v[28:29], v[168:169]
	s_cmp_le_u32 s20, 15
	s_cbranch_scc1 .Ls5c_done
	v_xor_b32_e32 v28, 0x80000000, v87
	v_mov_b32_e32 v29, v86
	v_pk_mul_f32 v[28:29], v[6:7], v[28:29]
	s_nop 0
	v_pk_fma_f32 v[28:29], v[8:9], v[86:87], v[28:29]
	s_nop 0
	v_pk_add_f32 v[86:87], v[28:29], v[170:171]
	s_cmp_le_u32 s20, 16
	s_cbranch_scc1 .Ls5c_done
	v_xor_b32_e32 v28, 0x80000000, v87
	v_mov_b32_e32 v29, v86
	v_pk_mul_f32 v[28:29], v[6:7], v[28:29]
	s_nop 0
	v_pk_fma_f32 v[28:29], v[8:9], v[86:87], v[28:29]
	s_nop 0
	v_pk_add_f32 v[86:87], v[28:29], v[180:181]
	s_cmp_le_u32 s20, 17
	s_cbranch_scc1 .Ls5c_done
	v_xor_b32_e32 v28, 0x80000000, v87
	v_mov_b32_e32 v29, v86
	v_pk_mul_f32 v[28:29], v[6:7], v[28:29]
	s_nop 0
	v_pk_fma_f32 v[28:29], v[8:9], v[86:87], v[28:29]
	s_nop 0
	v_pk_add_f32 v[86:87], v[28:29], v[182:183]
	s_cmp_le_u32 s20, 18
	s_cbranch_scc1 .Ls5c_done
	v_xor_b32_e32 v28, 0x80000000, v87
	v_mov_b32_e32 v29, v86
	v_pk_mul_f32 v[28:29], v[6:7], v[28:29]
	s_nop 0
	v_pk_fma_f32 v[28:29], v[8:9], v[86:87], v[28:29]
	s_nop 0
	v_pk_add_f32 v[86:87], v[28:29], v[184:185]
	s_cmp_le_u32 s20, 19
	s_cbranch_scc1 .Ls5c_done
	v_xor_b32_e32 v28, 0x80000000, v87
	v_mov_b32_e32 v29, v86
	v_pk_mul_f32 v[28:29], v[6:7], v[28:29]
	s_nop 0
	v_pk_fma_f32 v[28:29], v[8:9], v[86:87], v[28:29]
	s_nop 0
	v_pk_add_f32 v[86:87], v[28:29], v[186:187]
	s_cmp_le_u32 s20, 20
	s_cbranch_scc1 .Ls5c_done
	v_xor_b32_e32 v28, 0x80000000, v87
	v_mov_b32_e32 v29, v86
	v_pk_mul_f32 v[28:29], v[6:7], v[28:29]
	s_nop 0
	v_pk_fma_f32 v[28:29], v[8:9], v[86:87], v[28:29]
	s_nop 0
	v_pk_add_f32 v[86:87], v[28:29], v[188:189]
	s_cmp_le_u32 s20, 21
	s_cbranch_scc1 .Ls5c_done
	v_xor_b32_e32 v28, 0x80000000, v87
	v_mov_b32_e32 v29, v86
	v_pk_mul_f32 v[28:29], v[6:7], v[28:29]
	s_nop 0
	v_pk_fma_f32 v[28:29], v[8:9], v[86:87], v[28:29]
	s_nop 0
	v_pk_add_f32 v[86:87], v[28:29], v[190:191]
	s_cmp_le_u32 s20, 22
	s_cbranch_scc1 .Ls5c_done
	v_xor_b32_e32 v28, 0x80000000, v87
	v_mov_b32_e32 v29, v86
	v_pk_mul_f32 v[28:29], v[6:7], v[28:29]
	s_nop 0
	v_pk_fma_f32 v[28:29], v[8:9], v[86:87], v[28:29]
	s_nop 0
	v_pk_add_f32 v[86:87], v[28:29], v[192:193]
	s_cmp_le_u32 s20, 23
	s_cbranch_scc1 .Ls5c_done
	v_xor_b32_e32 v28, 0x80000000, v87
	v_mov_b32_e32 v29, v86
	v_pk_mul_f32 v[28:29], v[6:7], v[28:29]
	s_nop 0
	v_pk_fma_f32 v[28:29], v[8:9], v[86:87], v[28:29]
	s_nop 0
	v_pk_add_f32 v[86:87], v[28:29], v[194:195]
	s_cmp_le_u32 s20, 24
	s_cbranch_scc1 .Ls5c_done
	v_xor_b32_e32 v28, 0x80000000, v87
	v_mov_b32_e32 v29, v86
	v_pk_mul_f32 v[28:29], v[6:7], v[28:29]
	s_nop 0
	v_pk_fma_f32 v[28:29], v[8:9], v[86:87], v[28:29]
	s_nop 0
	v_pk_add_f32 v[86:87], v[28:29], v[196:197]
	s_cmp_le_u32 s20, 25
	s_cbranch_scc1 .Ls5c_done
	v_xor_b32_e32 v28, 0x80000000, v87
	v_mov_b32_e32 v29, v86
	v_pk_mul_f32 v[28:29], v[6:7], v[28:29]
	s_nop 0
	v_pk_fma_f32 v[28:29], v[8:9], v[86:87], v[28:29]
	s_nop 0
	v_pk_add_f32 v[86:87], v[28:29], v[198:199]
	s_cmp_le_u32 s20, 26
	s_cbranch_scc1 .Ls5c_done
	v_xor_b32_e32 v28, 0x80000000, v87
	v_mov_b32_e32 v29, v86
	v_pk_mul_f32 v[28:29], v[6:7], v[28:29]
	s_nop 0
	v_pk_fma_f32 v[28:29], v[8:9], v[86:87], v[28:29]
	s_nop 0
	v_pk_add_f32 v[86:87], v[28:29], v[200:201]
	s_cmp_le_u32 s20, 27
	s_cbranch_scc1 .Ls5c_done
	v_xor_b32_e32 v28, 0x80000000, v87
	v_mov_b32_e32 v29, v86
	v_pk_mul_f32 v[28:29], v[6:7], v[28:29]
	s_nop 0
	v_pk_fma_f32 v[28:29], v[8:9], v[86:87], v[28:29]
	s_nop 0
	v_pk_add_f32 v[86:87], v[28:29], v[202:203]
	s_cmp_le_u32 s20, 28
	s_cbranch_scc1 .Ls5c_done
	v_xor_b32_e32 v28, 0x80000000, v87
	v_mov_b32_e32 v29, v86
	v_pk_mul_f32 v[28:29], v[6:7], v[28:29]
	s_nop 0
	v_pk_fma_f32 v[28:29], v[8:9], v[86:87], v[28:29]
	s_nop 0
	v_pk_add_f32 v[86:87], v[28:29], v[204:205]
	s_cmp_le_u32 s20, 29
	s_cbranch_scc1 .Ls5c_done
	v_xor_b32_e32 v28, 0x80000000, v87
	v_mov_b32_e32 v29, v86
	v_pk_mul_f32 v[28:29], v[6:7], v[28:29]
	s_nop 0
	v_pk_fma_f32 v[28:29], v[8:9], v[86:87], v[28:29]
	s_nop 0
	v_pk_add_f32 v[86:87], v[28:29], v[206:207]
	s_cmp_le_u32 s20, 30
	s_cbranch_scc1 .Ls5c_done
	v_xor_b32_e32 v28, 0x80000000, v87
	v_mov_b32_e32 v29, v86
	v_pk_mul_f32 v[28:29], v[6:7], v[28:29]
	s_nop 0
	v_pk_fma_f32 v[28:29], v[8:9], v[86:87], v[28:29]
	s_nop 0
	v_pk_add_f32 v[86:87], v[28:29], v[208:209]
.Ls5c_done:
.LBB0_709:
	s_or_b64 exec, exec, s[2:3]
	v_mov_b32_e32 v233, v30
